# out-projection K-loop: the eight two-step VALU address adds per iteration replaced by scalar-base loads (all four GEMM K-loops now converted)
# speedup vs baseline: 1.0056x; 1.0056x over previous
; #define PG8_STAGE(bufoff, gbase, voff) do { _Pragma("unroll") for (int _i = 0; _i < 2; ++_i) \
;         __builtin_amdgcn_global_load_lds((const unsigned*)((const char*)(gbase) + (voff)[_i]), (PG8_LAS unsigned*)(lds + (bufoff) + ldsw + _i * 8192), 16, 0, 0); } while (0)
; #define PG8_LDA(dst, b, h) do { _Pragma("unroll") for (int m = 0; m < 4; ++m) _Pragma("unroll") for (int k = 0; k < 2; ++k) dst[m][k] = *(const PG8_LAS bf16x8*)(lds + PG8_SA(b, h) + aoff + m * 2048 + k * 1024); } while (0)
; #define PG8_LDB(dst, b, h) do { _Pragma("unroll") for (int n = 0; n < 2; ++n) _Pragma("unroll") for (int k = 0; k < 2; ++k) dst[n][k] = *(const PG8_LAS bf16x8*)(lds + PG8_SB(b, h) + boff + n * 2048 + k * 1024); } while (0)
; #define PG8_WAIT_V(n) asm volatile("s_waitcnt vmcnt(" #n ")" ::: "memory")
; #define PG8_WAIT_L(n) asm volatile("s_waitcnt lgkmcnt(" #n ")" ::: "memory")
; #define PG8_BAR __builtin_amdgcn_s_barrier()
; #define PG8_SCHED __builtin_amdgcn_sched_barrier(0)
; template <class Epi, class Sched, bool ALIGN_EPI = false, bool SP2 = false>
; __device__ __forceinline__ void gemm_phase(PG8_LAS unsigned char* lds, const Gemm g, const Sched& S, const Epi& E) {
;     ...
;         const bool has_next = S.next(ui + 1, nxt);
;         const char* nA = has_next ? (const char*)g.A + (size_t)nxt.pm * tstep : cA; const char* nB = has_next ? (const char*)g.Bt + (size_t)nxt.pn * tstep : cB;
;         for (int t = 0; t < nt; t += 2) {
;             const bool last = (t == nt - 2);
;             const char* a1 = cA + (size_t)(t + 1) * kstep;
;             const char* a2 = last ? nA : cA + (size_t)(t + 2) * kstep; const char* b2 = last ? nB : cB + (size_t)(t + 2) * kstep;
;             const char* a3 = a2 + kstep; const char* b3 = b2 + kstep;
;             if (last && has_next) S.a_ready(nxt);
;             if constexpr (SP2) {
;             PG8_LDB(B0, 0, 0); PG8_LDB(B1, 0, 1); PG8_SCHED; PG8_LDA(At, 0, 0); PG8_STAGE(PG8_SA(1, 1), a1 + hstep, voffA);
;             PG8_WAIT_V(8); PG8_WAIT_L(0); PG8_BAR; PG8_MMA(0, 0, At, B0); PG8_MMA(0, 1, At, B1); PG8_BAR; PG8_SCHED;
;             PG8_LDA(At, 0, 1); PG8_STAGE(PG8_SB(0, 0), b2, voffB); PG8_STAGE(PG8_SB(0, 1), b2 + hstep, voffB); PG8_STAGE(PG8_SA(0, 0), a2, voffA);
;             PG8_WAIT_V(8); PG8_WAIT_L(0); PG8_BAR; PG8_MMA(1, 0, At, B0); PG8_MMA(1, 1, At, B1); PG8_BAR; PG8_SCHED;
.LBB0_2046:
	s_add_u32 s20, s44, 0xfff80080
	s_addc_u32 s21, s45, -1
	s_add_i32 s30, 0, 0x10000
	s_cmp_eq_u32 s59, 28
	s_cselect_b32 s47, s12, s21
	s_cselect_b32 s46, s13, s20
	s_cselect_b32 s21, s23, s58
	s_cselect_b32 s20, s25, s33
	s_add_i32 s60, 0, 0x14000
	s_waitcnt vmcnt(0) lgkmcnt(0)
	v_add_u32_e32 v80, s30, v212
	v_add_u32_e32 v160, s60, v212
	ds_read_b128 v[60:63], v80
	ds_read_b128 v[64:67], v80 offset:1024
	ds_read_b128 v[76:79], v80 offset:2048
	ds_read_b128 v[80:83], v80 offset:3072
	ds_read_b128 v[148:151], v160
	ds_read_b128 v[152:155], v160 offset:1024
	ds_read_b128 v[156:159], v160 offset:2048
	ds_read_b128 v[160:163], v160 offset:3072
	s_add_i32 m0, s43, 0xc000
	ds_read_b128 v[164:167], v218
	ds_read_b128 v[168:171], v218 offset:1024
	ds_read_b128 v[172:175], v218 offset:2048
	ds_read_b128 v[176:179], v218 offset:3072
	ds_read_b128 v[190:193], v218 offset:4096
	ds_read_b128 v[194:197], v218 offset:5120
	ds_read_b128 v[198:201], v218 offset:6144
	ds_read_b128 v[202:205], v218 offset:7168
	global_load_lds_dwordx4 v188, s[44:45]
	s_add_i32 m0, s43, 0xe000
	s_nop 0
	global_load_lds_dwordx4 v186, s[44:45]
	s_waitcnt vmcnt(8)
	s_waitcnt lgkmcnt(0)
	s_barrier
	s_setprio 1
	s_waitcnt lgkmcnt(0)
	v_mfma_f32_16x16x32_bf16 v[144:147], v[60:63], v[164:167], v[144:147]
	v_mfma_f32_16x16x32_bf16 v[140:143], v[76:79], v[164:167], v[140:143]
	v_mfma_f32_16x16x32_bf16 v[136:139], v[60:63], v[172:175], v[136:139]
	v_mfma_f32_16x16x32_bf16 v[132:135], v[76:79], v[172:175], v[132:135]
	v_mfma_f32_16x16x32_bf16 v[112:115], v[60:63], v[190:193], v[112:115]
	v_mfma_f32_16x16x32_bf16 v[108:111], v[76:79], v[190:193], v[108:111]
	v_mfma_f32_16x16x32_bf16 v[104:107], v[60:63], v[198:201], v[104:107]
	v_mfma_f32_16x16x32_bf16 v[100:103], v[76:79], v[198:201], v[100:103]
	v_mfma_f32_16x16x32_bf16 v[144:147], v[64:67], v[168:171], v[144:147]
	v_mfma_f32_16x16x32_bf16 v[140:143], v[80:83], v[168:171], v[140:143]
	v_mfma_f32_16x16x32_bf16 v[136:139], v[64:67], v[176:179], v[136:139]
	v_mfma_f32_16x16x32_bf16 v[132:135], v[80:83], v[176:179], v[132:135]
	v_mfma_f32_16x16x32_bf16 v[112:115], v[64:67], v[194:197], v[112:115]
	v_mfma_f32_16x16x32_bf16 v[108:111], v[80:83], v[194:197], v[108:111]
	v_mfma_f32_16x16x32_bf16 v[104:107], v[64:67], v[202:205], v[104:107]
	v_mfma_f32_16x16x32_bf16 v[100:103], v[80:83], v[202:205], v[100:103]
	s_setprio 0
	s_setprio 1
	v_mfma_f32_16x16x32_bf16 v[128:131], v[148:151], v[164:167], v[128:131]
	v_mfma_f32_16x16x32_bf16 v[124:127], v[156:159], v[164:167], v[124:127]
	v_mfma_f32_16x16x32_bf16 v[120:123], v[148:151], v[172:175], v[120:123]
	v_mfma_f32_16x16x32_bf16 v[116:119], v[156:159], v[172:175], v[116:119]
	v_mfma_f32_16x16x32_bf16 v[96:99], v[148:151], v[190:193], v[96:99]
	v_mfma_f32_16x16x32_bf16 v[92:95], v[156:159], v[190:193], v[92:95]
	v_mfma_f32_16x16x32_bf16 v[88:91], v[148:151], v[198:201], v[88:91]
	v_mfma_f32_16x16x32_bf16 v[84:87], v[156:159], v[198:201], v[84:87]
	v_mfma_f32_16x16x32_bf16 v[128:131], v[152:155], v[168:171], v[128:131]
	v_mfma_f32_16x16x32_bf16 v[124:127], v[160:163], v[168:171], v[124:127]
	v_mfma_f32_16x16x32_bf16 v[120:123], v[152:155], v[176:179], v[120:123]
	v_mfma_f32_16x16x32_bf16 v[116:119], v[160:163], v[176:179], v[116:119]
	v_mfma_f32_16x16x32_bf16 v[96:99], v[152:155], v[194:197], v[96:99]
	v_mfma_f32_16x16x32_bf16 v[92:95], v[160:163], v[194:197], v[92:95]
	v_mfma_f32_16x16x32_bf16 v[88:91], v[152:155], v[202:205], v[88:91]
	v_mfma_f32_16x16x32_bf16 v[84:87], v[160:163], v[202:205], v[84:87]
	s_setprio 0
	s_barrier
	s_add_i32 s30, s30, s9
	s_mov_b32 m0, s30
	ds_read_b128 v[164:167], v218 offset:16384
	ds_read_b128 v[168:171], v218 offset:17408
	ds_read_b128 v[172:175], v218 offset:18432
	ds_read_b128 v[176:179], v218 offset:19456
	ds_read_b128 v[190:193], v218 offset:20480
	ds_read_b128 v[194:197], v218 offset:21504
	ds_read_b128 v[198:201], v218 offset:22528
	ds_read_b128 v[202:205], v218 offset:23552
	global_load_lds_dwordx4 v2, s[20:21]
	s_add_i32 m0, s30, 0x2000
	s_add_u32 s30, s20, 0x80000
	s_addc_u32 s31, s21, 0
	s_add_u32 s98, s20, s28
	s_addc_u32 s99, s21, s29
	s_add_u32 s94, s46, s28
	s_addc_u32 s95, s47, s29
	s_add_i32 s60, s60, s9
	global_load_lds_dwordx4 v184, s[20:21]
	s_mov_b32 m0, s60
	s_nop 0
	global_load_lds_dwordx4 v2, s[30:31]
	s_add_i32 m0, s60, 0x2000
	s_nop 0
	global_load_lds_dwordx4 v184, s[30:31]
	s_mov_b32 m0, s43
	s_nop 0
	global_load_lds_dwordx4 v180, s[46:47]
	s_mov_b32 m0, s50
	s_nop 0
	global_load_lds_dwordx4 v182, s[46:47]
	s_waitcnt vmcnt(8)
	s_waitcnt lgkmcnt(0)
	s_barrier
; #define PG8_STAGE(bufoff, gbase, voff) do { _Pragma("unroll") for (int _i = 0; _i < 2; ++_i) \
;         __builtin_amdgcn_global_load_lds((const unsigned*)((const char*)(gbase) + (voff)[_i]), (PG8_LAS unsigned*)(lds + (bufoff) + ldsw + _i * 8192), 16, 0, 0); } while (0)
; #define PG8_LDA(dst, b, h) do { _Pragma("unroll") for (int m = 0; m < 4; ++m) _Pragma("unroll") for (int k = 0; k < 2; ++k) dst[m][k] = *(const PG8_LAS bf16x8*)(lds + PG8_SA(b, h) + aoff + m * 2048 + k * 1024); } while (0)
; #define PG8_LDB(dst, b, h) do { _Pragma("unroll") for (int n = 0; n < 2; ++n) _Pragma("unroll") for (int k = 0; k < 2; ++k) dst[n][k] = *(const PG8_LAS bf16x8*)(lds + PG8_SB(b, h) + boff + n * 2048 + k * 1024); } while (0)
; #define PG8_MMA(ai, bj, At, Bt) do { __builtin_amdgcn_s_setprio(1); _Pragma("unroll") for (int m = 0; m < 4; ++m) _Pragma("unroll") for (int n = 0; n < 2; ++n) _Pragma("unroll") for (int k = 0; k < 2; ++k) \
;         acc[ai][bj][m][n] = __builtin_amdgcn_mfma_f32_16x16x32_bf16(Bt[n][k], At[m][k], acc[ai][bj][m][n], 0, 0, 0); __builtin_amdgcn_s_setprio(0); } while (0)
; #define PG8_WAIT_V(n) asm volatile("s_waitcnt vmcnt(" #n ")" ::: "memory")
; #define PG8_WAIT_L(n) asm volatile("s_waitcnt lgkmcnt(" #n ")" ::: "memory")
; #define PG8_BAR __builtin_amdgcn_s_barrier()
; #define PG8_SCHED __builtin_amdgcn_sched_barrier(0)
; template <class Epi, class Sched, bool ALIGN_EPI = false, bool SP2 = false>
; __device__ __forceinline__ void gemm_phase(PG8_LAS unsigned char* lds, const Gemm g, const Sched& S, const Epi& E) {
;     ...
;             PG8_WAIT_V(8); PG8_WAIT_L(0); PG8_BAR; PG8_MMA(1, 0, At, B0); PG8_MMA(1, 1, At, B1); PG8_BAR; PG8_SCHED;
;             PG8_LDB(B0, 1, 0); PG8_LDB(B1, 1, 1); PG8_SCHED; PG8_LDA(At, 1, 0); PG8_STAGE(PG8_SA(0, 1), a2 + hstep, voffA);
;             PG8_WAIT_V(8); PG8_WAIT_L(0); PG8_BAR; PG8_MMA(0, 0, At, B0); PG8_MMA(0, 1, At, B1); PG8_BAR; PG8_SCHED;
	s_setprio 1
	s_waitcnt lgkmcnt(0)
	v_mfma_f32_16x16x32_bf16 v[72:75], v[60:63], v[164:167], v[72:75]
	v_mfma_f32_16x16x32_bf16 v[68:71], v[76:79], v[164:167], v[68:71]
	v_mfma_f32_16x16x32_bf16 v[56:59], v[60:63], v[172:175], v[56:59]
	v_mfma_f32_16x16x32_bf16 v[52:55], v[76:79], v[172:175], v[52:55]
	v_mfma_f32_16x16x32_bf16 v[32:35], v[60:63], v[190:193], v[32:35]
	v_mfma_f32_16x16x32_bf16 v[28:31], v[76:79], v[190:193], v[28:31]
	v_mfma_f32_16x16x32_bf16 v[24:27], v[60:63], v[198:201], v[24:27]
	v_mfma_f32_16x16x32_bf16 v[20:23], v[76:79], v[198:201], v[20:23]
	v_mfma_f32_16x16x32_bf16 v[72:75], v[64:67], v[168:171], v[72:75]
	v_mfma_f32_16x16x32_bf16 v[68:71], v[80:83], v[168:171], v[68:71]
	v_mfma_f32_16x16x32_bf16 v[56:59], v[64:67], v[176:179], v[56:59]
	v_mfma_f32_16x16x32_bf16 v[52:55], v[80:83], v[176:179], v[52:55]
	v_mfma_f32_16x16x32_bf16 v[32:35], v[64:67], v[194:197], v[32:35]
	v_mfma_f32_16x16x32_bf16 v[28:31], v[80:83], v[194:197], v[28:31]
	v_mfma_f32_16x16x32_bf16 v[24:27], v[64:67], v[202:205], v[24:27]
	v_mfma_f32_16x16x32_bf16 v[20:23], v[80:83], v[202:205], v[20:23]
	s_setprio 0
	s_setprio 1
	v_mfma_f32_16x16x32_bf16 v[48:51], v[148:151], v[164:167], v[48:51]
	v_mfma_f32_16x16x32_bf16 v[44:47], v[156:159], v[164:167], v[44:47]
	v_mfma_f32_16x16x32_bf16 v[40:43], v[148:151], v[172:175], v[40:43]
	v_mfma_f32_16x16x32_bf16 v[36:39], v[156:159], v[172:175], v[36:39]
	v_mfma_f32_16x16x32_bf16 v[16:19], v[148:151], v[190:193], v[16:19]
	v_mfma_f32_16x16x32_bf16 v[12:15], v[156:159], v[190:193], v[12:15]
	v_mfma_f32_16x16x32_bf16 v[8:11], v[148:151], v[198:201], v[8:11]
	v_mfma_f32_16x16x32_bf16 v[4:7], v[156:159], v[198:201], v[4:7]
	v_mfma_f32_16x16x32_bf16 v[48:51], v[152:155], v[168:171], v[48:51]
	v_mfma_f32_16x16x32_bf16 v[44:47], v[160:163], v[168:171], v[44:47]
	v_mfma_f32_16x16x32_bf16 v[40:43], v[152:155], v[176:179], v[40:43]
	v_mfma_f32_16x16x32_bf16 v[36:39], v[160:163], v[176:179], v[36:39]
	v_mfma_f32_16x16x32_bf16 v[16:19], v[152:155], v[194:197], v[16:19]
	v_mfma_f32_16x16x32_bf16 v[12:15], v[160:163], v[194:197], v[12:15]
	v_mfma_f32_16x16x32_bf16 v[8:11], v[152:155], v[202:205], v[8:11]
	v_mfma_f32_16x16x32_bf16 v[4:7], v[160:163], v[202:205], v[4:7]
	s_setprio 0
	s_barrier
	s_add_i32 s60, 0, 0x18000
	s_add_i32 s61, 0, 0x1c000
	v_add_u32_e32 v80, s60, v212
	v_add_u32_e32 v160, s61, v212
	ds_read_b128 v[60:63], v80
	ds_read_b128 v[64:67], v80 offset:1024
	ds_read_b128 v[76:79], v80 offset:2048
	ds_read_b128 v[80:83], v80 offset:3072
	ds_read_b128 v[148:151], v160
	ds_read_b128 v[152:155], v160 offset:1024
	ds_read_b128 v[156:159], v160 offset:2048
	ds_read_b128 v[160:163], v160 offset:3072
	s_add_u32 s30, s46, 0x80000
	s_addc_u32 s31, s47, 0
	s_mov_b32 m0, s51
	ds_read_b128 v[164:167], v218 offset:32768
	ds_read_b128 v[168:171], v218 offset:33792
	ds_read_b128 v[172:175], v218 offset:34816
	ds_read_b128 v[176:179], v218 offset:35840
	ds_read_b128 v[190:193], v218 offset:36864
	ds_read_b128 v[194:197], v218 offset:37888
	ds_read_b128 v[198:201], v218 offset:38912
	ds_read_b128 v[202:205], v218 offset:39936
	global_load_lds_dwordx4 v180, s[30:31]
	s_mov_b32 m0, s52
	s_nop 0
	global_load_lds_dwordx4 v182, s[30:31]
	s_waitcnt vmcnt(8)
	s_waitcnt lgkmcnt(0)
	s_barrier
	s_setprio 1
	s_waitcnt lgkmcnt(0)
	v_mfma_f32_16x16x32_bf16 v[144:147], v[60:63], v[164:167], v[144:147]
	v_mfma_f32_16x16x32_bf16 v[140:143], v[76:79], v[164:167], v[140:143]
	v_mfma_f32_16x16x32_bf16 v[136:139], v[60:63], v[172:175], v[136:139]
	v_mfma_f32_16x16x32_bf16 v[132:135], v[76:79], v[172:175], v[132:135]
	v_mfma_f32_16x16x32_bf16 v[112:115], v[60:63], v[190:193], v[112:115]
	v_mfma_f32_16x16x32_bf16 v[108:111], v[76:79], v[190:193], v[108:111]
	v_mfma_f32_16x16x32_bf16 v[104:107], v[60:63], v[198:201], v[104:107]
	v_mfma_f32_16x16x32_bf16 v[100:103], v[76:79], v[198:201], v[100:103]
	v_mfma_f32_16x16x32_bf16 v[144:147], v[64:67], v[168:171], v[144:147]
	v_mfma_f32_16x16x32_bf16 v[140:143], v[80:83], v[168:171], v[140:143]
	v_mfma_f32_16x16x32_bf16 v[136:139], v[64:67], v[176:179], v[136:139]
	v_mfma_f32_16x16x32_bf16 v[132:135], v[80:83], v[176:179], v[132:135]
	v_mfma_f32_16x16x32_bf16 v[112:115], v[64:67], v[194:197], v[112:115]
	v_mfma_f32_16x16x32_bf16 v[108:111], v[80:83], v[194:197], v[108:111]
	v_mfma_f32_16x16x32_bf16 v[104:107], v[64:67], v[202:205], v[104:107]
	v_mfma_f32_16x16x32_bf16 v[100:103], v[80:83], v[202:205], v[100:103]
	s_setprio 0
	s_setprio 1
	v_mfma_f32_16x16x32_bf16 v[128:131], v[148:151], v[164:167], v[128:131]
	v_mfma_f32_16x16x32_bf16 v[124:127], v[156:159], v[164:167], v[124:127]
	v_mfma_f32_16x16x32_bf16 v[120:123], v[148:151], v[172:175], v[120:123]
	v_mfma_f32_16x16x32_bf16 v[116:119], v[156:159], v[172:175], v[116:119]
	v_mfma_f32_16x16x32_bf16 v[96:99], v[148:151], v[190:193], v[96:99]
	v_mfma_f32_16x16x32_bf16 v[92:95], v[156:159], v[190:193], v[92:95]
	v_mfma_f32_16x16x32_bf16 v[88:91], v[148:151], v[198:201], v[88:91]
	v_mfma_f32_16x16x32_bf16 v[84:87], v[156:159], v[198:201], v[84:87]
	v_mfma_f32_16x16x32_bf16 v[128:131], v[152:155], v[168:171], v[128:131]
	v_mfma_f32_16x16x32_bf16 v[124:127], v[160:163], v[168:171], v[124:127]
	v_mfma_f32_16x16x32_bf16 v[120:123], v[152:155], v[176:179], v[120:123]
	v_mfma_f32_16x16x32_bf16 v[116:119], v[160:163], v[176:179], v[116:119]
	v_mfma_f32_16x16x32_bf16 v[96:99], v[152:155], v[194:197], v[96:99]
	v_mfma_f32_16x16x32_bf16 v[92:95], v[160:163], v[194:197], v[92:95]
	v_mfma_f32_16x16x32_bf16 v[88:91], v[152:155], v[202:205], v[88:91]
	v_mfma_f32_16x16x32_bf16 v[84:87], v[160:163], v[202:205], v[84:87]
	s_setprio 0
	s_barrier
;     __device__ __forceinline__ void operator()(const f32x4 (&acc)[2][2][4][2], const Unit& u, int wr, int wc, int fr, int fq) const {
;         const int row0 = u.pm * BM + wr * 64 + fr; const int col0 = u.pn * BM + wc * 32 + 8 * fq;
;         const float* gp = gate + (size_t)((u.pm * BM) >> 12) * gstride + col0;
;         f32x4 gv[2][2];
; #pragma unroll
;         for (int bj = 0; bj < 2; ++bj)
; #pragma unroll
;             for (int n = 0; n < 2; ++n) gv[bj][n] = *(const f32x4*)(gp + bj * HALF + n * 4);
;         if (base_f32) { const float* bp = (const float*)base;
; #pragma unroll
;             for (int ai = 0; ai < 2; ++ai)
; #pragma unroll
;                 for (int m2 = 0; m2 < 2; ++m2) { f32x4 bs[2][2][2];
; #pragma unroll
;                     for (int mm = 0; mm < 2; ++mm) { const size_t off = (size_t)(row0 + ai * HALF + (2 * m2 + mm) * 16) * ldc + col0;
; #pragma unroll
;                         for (int bj = 0; bj < 2; ++bj)
; #pragma unroll
;                             for (int n = 0; n < 2; ++n) bs[mm][bj][n] = *(const f32x4*)(bp + off + bj * HALF + n * 4); }
; #pragma unroll
;                     for (int mm = 0; mm < 2; ++mm) { const size_t off = (size_t)(row0 + ai * HALF + (2 * m2 + mm) * 16) * ldc + col0;
; #pragma unroll
;                         for (int bj = 0; bj < 2; ++bj) { const f32x4 v0 = bs[mm][bj][0] + gv[bj][0] * acc[ai][bj][2 * m2 + mm][0], v1 = bs[mm][bj][1] + gv[bj][1] * acc[ai][bj][2 * m2 + mm][1];
;                             u32x4 w; w.x = cvt_pk_bf16(v0[0], v0[1]); w.y = cvt_pk_bf16(v0[2], v0[3]); w.z = cvt_pk_bf16(v1[0], v1[1]); w.w = cvt_pk_bf16(v1[2], v1[3]);
;                             *(u32x4*)(out + off + bj * HALF) = w; } }
;                     asm volatile("" ::: "memory"); }
;         } else { const bf16_t* bp = (const bf16_t*)base;
; #pragma unroll
;             for (int ai = 0; ai < 2; ++ai) { u32x4 bs[4][2];
; #pragma unroll
; template <class Epi, class Sched, bool ALIGN_EPI = false, bool SP2 = false>
; __device__ __forceinline__ void gemm_phase(PG8_LAS unsigned char* lds, const Gemm g, const Sched& S, const Epi& E) {
;     ...
;             PG8_LDA(At, 1, 1); PG8_STAGE(PG8_SB(1, 0), b3, voffB); PG8_STAGE(PG8_SB(1, 1), b3 + hstep, voffB); PG8_STAGE(PG8_SA(1, 0), a3, voffA);
;             PG8_WAIT_V(8); PG8_WAIT_L(0); PG8_BAR; PG8_MMA(1, 0, At, B0); PG8_MMA(1, 1, At, B1); PG8_BAR; PG8_SCHED;
	s_add_i32 s30, s60, s9
	s_mov_b32 m0, s30
	ds_read_b128 v[164:167], v218 offset:49152
	ds_read_b128 v[168:171], v218 offset:50176
	ds_read_b128 v[172:175], v218 offset:51200
	ds_read_b128 v[176:179], v218 offset:52224
	ds_read_b128 v[190:193], v218 offset:53248
	ds_read_b128 v[194:197], v218 offset:54272
	ds_read_b128 v[198:201], v218 offset:55296
	ds_read_b128 v[202:205], v218 offset:56320
	global_load_lds_dwordx4 v2, s[98:99]
	s_add_i32 m0, s30, 0x2000
	s_add_u32 s20, s20, 0x80080
	s_addc_u32 s21, s21, 0
	s_add_i32 s30, s61, s9
	global_load_lds_dwordx4 v184, s[98:99]
	s_mov_b32 m0, s30
	s_nop 0
	global_load_lds_dwordx4 v2, s[20:21]
	s_add_i32 m0, s30, 0x2000
	s_nop 0
	global_load_lds_dwordx4 v184, s[20:21]
	s_mov_b32 m0, s54
	s_nop 0
	global_load_lds_dwordx4 v180, s[94:95]
	s_mov_b32 m0, s55
	s_nop 0
	global_load_lds_dwordx4 v182, s[94:95]
	s_waitcnt vmcnt(8)
	s_waitcnt lgkmcnt(0)
	s_barrier
	s_setprio 1
	s_waitcnt lgkmcnt(0)
	v_mfma_f32_16x16x32_bf16 v[72:75], v[60:63], v[164:167], v[72:75]
	v_mfma_f32_16x16x32_bf16 v[68:71], v[76:79], v[164:167], v[68:71]
	v_mfma_f32_16x16x32_bf16 v[56:59], v[60:63], v[172:175], v[56:59]
	v_mfma_f32_16x16x32_bf16 v[52:55], v[76:79], v[172:175], v[52:55]
	v_mfma_f32_16x16x32_bf16 v[32:35], v[60:63], v[190:193], v[32:35]
	v_mfma_f32_16x16x32_bf16 v[28:31], v[76:79], v[190:193], v[28:31]
	v_mfma_f32_16x16x32_bf16 v[24:27], v[60:63], v[198:201], v[24:27]
	v_mfma_f32_16x16x32_bf16 v[20:23], v[76:79], v[198:201], v[20:23]
	v_mfma_f32_16x16x32_bf16 v[72:75], v[64:67], v[168:171], v[72:75]
	v_mfma_f32_16x16x32_bf16 v[68:71], v[80:83], v[168:171], v[68:71]
	v_mfma_f32_16x16x32_bf16 v[56:59], v[64:67], v[176:179], v[56:59]
	v_mfma_f32_16x16x32_bf16 v[52:55], v[80:83], v[176:179], v[52:55]
	v_mfma_f32_16x16x32_bf16 v[32:35], v[64:67], v[194:197], v[32:35]
	v_mfma_f32_16x16x32_bf16 v[28:31], v[80:83], v[194:197], v[28:31]
	v_mfma_f32_16x16x32_bf16 v[24:27], v[64:67], v[202:205], v[24:27]
	v_mfma_f32_16x16x32_bf16 v[20:23], v[80:83], v[202:205], v[20:23]
	s_setprio 0
	s_setprio 1
	v_mfma_f32_16x16x32_bf16 v[48:51], v[148:151], v[164:167], v[48:51]
	v_mfma_f32_16x16x32_bf16 v[44:47], v[156:159], v[164:167], v[44:47]
	v_mfma_f32_16x16x32_bf16 v[40:43], v[148:151], v[172:175], v[40:43]
	v_mfma_f32_16x16x32_bf16 v[36:39], v[156:159], v[172:175], v[36:39]
	v_mfma_f32_16x16x32_bf16 v[16:19], v[148:151], v[190:193], v[16:19]
	v_mfma_f32_16x16x32_bf16 v[12:15], v[156:159], v[190:193], v[12:15]
	v_mfma_f32_16x16x32_bf16 v[8:11], v[148:151], v[198:201], v[8:11]
	v_mfma_f32_16x16x32_bf16 v[4:7], v[156:159], v[198:201], v[4:7]
	v_mfma_f32_16x16x32_bf16 v[48:51], v[152:155], v[168:171], v[48:51]
	v_mfma_f32_16x16x32_bf16 v[44:47], v[160:163], v[168:171], v[44:47]
	v_mfma_f32_16x16x32_bf16 v[40:43], v[152:155], v[176:179], v[40:43]
	v_mfma_f32_16x16x32_bf16 v[36:39], v[160:163], v[176:179], v[36:39]
	v_mfma_f32_16x16x32_bf16 v[16:19], v[152:155], v[194:197], v[16:19]
	v_mfma_f32_16x16x32_bf16 v[12:15], v[160:163], v[194:197], v[12:15]
	v_mfma_f32_16x16x32_bf16 v[8:11], v[152:155], v[202:205], v[8:11]
	v_mfma_f32_16x16x32_bf16 v[4:7], v[160:163], v[202:205], v[4:7]
	s_setprio 0
	s_barrier
	s_add_i32 s59, s59, 2
	s_add_u32 s33, s33, 0x100
	s_addc_u32 s58, s58, 0
	s_add_u32 s44, s44, 0x100
	s_addc_u32 s45, s45, 0
	s_cmp_gt_u32 s59, 29
	s_cbranch_scc0 .LBB0_2046
	v_lshl_or_b32 v202, s4, 8, v213
	s_ashr_i32 s4, s42, 4
	s_mul_hi_i32 s13, s4, 0xc000
	s_mul_i32 s4, s4, 0xc000
	s_add_u32 s12, s18, s4
	s_addc_u32 s13, s53, s13
	v_ashrrev_i32_e32 v203, 31, v202
	v_lshl_add_u64 v[60:61], v[202:203], 2, s[12:13]
	flat_load_dwordx4 v[80:83], v[60:61]
	flat_load_dwordx4 v[76:79], v[60:61] offset:16
	flat_load_dwordx4 v[64:67], v[60:61] offset:512
	s_nop 0
	flat_load_dwordx4 v[60:63], v[60:61] offset:528
	v_lshl_add_u32 v192, s42, 8, v1
	v_ashrrev_i32_e32 v193, 31, v192
	v_or_b32_e32 v198, 16, v192
	v_or_b32_e32 v196, 32, v192
	v_or_b32_e32 v194, 48, v192
	v_lshlrev_b64 v[200:201], 11, v[192:193]
	s_and_b64 vcc, exec, s[16:17]
	v_lshlrev_b64 v[190:191], 1, v[202:203]
	v_ashrrev_i32_e32 v199, 31, v198
	v_ashrrev_i32_e32 v197, 31, v196
	v_ashrrev_i32_e32 v195, 31, v194
	s_cbranch_vccz .LBB0_2049
	v_lshl_add_u64 v[204:205], s[26:27], 0, v[190:191]
	v_lshlrev_b64 v[156:157], 1, v[200:201]
	v_lshl_add_u64 v[148:149], v[204:205], 0, v[156:157]
	v_lshlrev_b64 v[152:153], 12, v[198:199]
	flat_load_dwordx4 v[172:175], v[148:149]
	flat_load_dwordx4 v[168:171], v[148:149] offset:256
	v_lshl_add_u64 v[148:149], v[204:205], 0, v[152:153]
	flat_load_dwordx4 v[164:167], v[148:149]
	s_nop 0
	flat_load_dwordx4 v[148:151], v[148:149] offset:256
	v_lshlrev_b64 v[208:209], 12, v[196:197]
	v_lshlrev_b64 v[206:207], 12, v[194:195]
	v_lshl_add_u64 v[154:155], v[204:205], 0, v[208:209]
	v_lshl_add_u64 v[210:211], v[204:205], 0, v[206:207]
	v_lshl_add_u64 v[214:215], s[14:15], 0, v[156:157]
	v_lshl_add_u64 v[216:217], s[14:15], 0, v[152:153]
	flat_load_dwordx4 v[176:179], v[154:155]
	flat_load_dwordx4 v[160:163], v[154:155] offset:256
	flat_load_dwordx4 v[156:159], v[210:211]
	s_nop 0
	flat_load_dwordx4 v[152:155], v[210:211] offset:256
	v_lshl_add_u64 v[210:211], v[216:217], 0, v[190:191]
	v_lshl_add_u64 v[214:215], v[214:215], 0, v[190:191]
	s_mov_b64 s[12:13], 0x80000
	s_waitcnt vmcnt(0) lgkmcnt(0)
; __device__ __forceinline__ unsigned cvt_pk_bf16(float lo, float hi) { unsigned r; asm volatile("v_cvt_pk_bf16_f32 %0, %1, %2" : "=v"(r) : "v"(lo), "v"(hi)); return r; }
;     __device__ __forceinline__ void operator()(const f32x4 (&acc)[2][2][4][2], const Unit& u, int wr, int wc, int fr, int fq) const {
;     ...
;                 for (int m = 0; m < 4; ++m) { const size_t off = (size_t)(row0 + ai * HALF + m * 16) * ldc + col0;
; #pragma unroll
;                     for (int bj = 0; bj < 2; ++bj) { const u32x4 r = bs[m][bj]; const f32x4 a0 = acc[ai][bj][m][0], a1 = acc[ai][bj][m][1];
;                         u32x4 w;
;                         w.x = cvt_pk_bf16(__builtin_bit_cast(float, r.x << 16) + gv[bj][0][0] * a0[0], __builtin_bit_cast(float, r.x & 0xffff0000u) + gv[bj][0][1] * a0[1]);
;                         w.y = cvt_pk_bf16(__builtin_bit_cast(float, r.y << 16) + gv[bj][0][2] * a0[2], __builtin_bit_cast(float, r.y & 0xffff0000u) + gv[bj][0][3] * a0[3]);
;                         w.z = cvt_pk_bf16(__builtin_bit_cast(float, r.z << 16) + gv[bj][1][0] * a1[0], __builtin_bit_cast(float, r.z & 0xffff0000u) + gv[bj][1][1] * a1[1]);
;                         w.w = cvt_pk_bf16(__builtin_bit_cast(float, r.w << 16) + gv[bj][1][2] * a1[2], __builtin_bit_cast(float, r.w & 0xffff0000u) + gv[bj][1][3] * a1[3]);
;                         *(u32x4*)(out + off + bj * HALF) = w; } }
	v_lshlrev_b32_e32 v216, 16, v172
	v_and_b32_e32 v172, 0xffff0000, v172
	v_lshlrev_b32_e32 v217, 16, v173
	v_and_b32_e32 v173, 0xffff0000, v173
	v_lshlrev_b32_e32 v219, 16, v174
	v_and_b32_e32 v174, 0xffff0000, v174
	v_lshlrev_b32_e32 v220, 16, v175
	v_and_b32_e32 v175, 0xffff0000, v175
	v_lshlrev_b32_e32 v221, 16, v168
	v_and_b32_e32 v168, 0xffff0000, v168
	v_lshlrev_b32_e32 v225, 16, v164
	v_and_b32_e32 v226, 0xffff0000, v164
	v_fmac_f32_e32 v216, v144, v80
	v_fmac_f32_e32 v172, v145, v81
	v_cvt_pk_bf16_f32 v164, v216, v172
	v_lshlrev_b32_e32 v222, 16, v169
	v_and_b32_e32 v169, 0xffff0000, v169
	v_lshlrev_b32_e32 v223, 16, v170
	v_and_b32_e32 v170, 0xffff0000, v170
	v_lshlrev_b32_e32 v224, 16, v171
	v_and_b32_e32 v171, 0xffff0000, v171
	v_lshlrev_b32_e32 v227, 16, v165
	v_and_b32_e32 v229, 0xffff0000, v165
	v_lshlrev_b32_e32 v232, 16, v166
	v_and_b32_e32 v233, 0xffff0000, v166
	v_lshlrev_b32_e32 v240, 16, v167
	v_and_b32_e32 v241, 0xffff0000, v167
	v_fmac_f32_e32 v217, v146, v82
	v_fmac_f32_e32 v173, v147, v83
	v_fmac_f32_e32 v219, v140, v76
	v_fmac_f32_e32 v174, v141, v77
	v_fmac_f32_e32 v220, v142, v78
	v_fmac_f32_e32 v175, v143, v79
	v_fmac_f32_e32 v221, v128, v64
	v_fmac_f32_e32 v168, v129, v65
	v_cvt_pk_bf16_f32 v165, v217, v173
	v_cvt_pk_bf16_f32 v166, v219, v174
	v_cvt_pk_bf16_f32 v167, v220, v175
	flat_store_dwordx4 v[214:215], v[164:167]
	v_fmac_f32_e32 v222, v130, v66
	v_fmac_f32_e32 v169, v131, v67
	v_cvt_pk_bf16_f32 v164, v221, v168
	v_fmac_f32_e32 v223, v124, v60
	v_fmac_f32_e32 v170, v125, v61
	v_fmac_f32_e32 v224, v126, v62
	v_fmac_f32_e32 v171, v127, v63
	v_fmac_f32_e32 v225, v136, v80
	v_fmac_f32_e32 v226, v137, v81
	v_cvt_pk_bf16_f32 v165, v222, v169
	v_cvt_pk_bf16_f32 v166, v223, v170
	v_cvt_pk_bf16_f32 v167, v224, v171
	flat_store_dwordx4 v[214:215], v[164:167] offset:256
	v_lshlrev_b32_e32 v242, 16, v148
	v_and_b32_e32 v148, 0xffff0000, v148
	v_cvt_pk_bf16_f32 v164, v225, v226
	v_fmac_f32_e32 v227, v138, v82
	v_fmac_f32_e32 v229, v139, v83
	v_fmac_f32_e32 v232, v132, v76
	v_fmac_f32_e32 v233, v133, v77
	v_fmac_f32_e32 v240, v134, v78
	v_fmac_f32_e32 v241, v135, v79
	v_cvt_pk_bf16_f32 v165, v227, v229
	v_cvt_pk_bf16_f32 v166, v232, v233
	v_cvt_pk_bf16_f32 v167, v240, v241
	flat_store_dwordx4 v[210:211], v[164:167]
	v_fmac_f32_e32 v148, v121, v65
	v_fmac_f32_e32 v242, v120, v64
	v_lshlrev_b32_e32 v164, 16, v149
	v_and_b32_e32 v149, 0xffff0000, v149
	v_fmac_f32_e32 v164, v122, v66
	v_fmac_f32_e32 v149, v123, v67
	v_cvt_pk_bf16_f32 v148, v242, v148
	v_cvt_pk_bf16_f32 v149, v164, v149
	v_lshlrev_b32_e32 v164, 16, v150
	v_and_b32_e32 v150, 0xffff0000, v150
	v_fmac_f32_e32 v164, v116, v60
	v_fmac_f32_e32 v150, v117, v61
	v_cvt_pk_bf16_f32 v150, v164, v150
	v_lshlrev_b32_e32 v164, 16, v151
	v_and_b32_e32 v151, 0xffff0000, v151
	v_fmac_f32_e32 v151, v119, v63
	v_fmac_f32_e32 v164, v118, v62
	v_cvt_pk_bf16_f32 v151, v164, v151
	flat_store_dwordx4 v[210:211], v[148:151] offset:256
	v_and_b32_e32 v164, 0xffff0000, v179
	v_fmac_f32_e32 v164, v111, v79
	v_lshlrev_b32_e32 v148, 16, v176
	v_and_b32_e32 v149, 0xffff0000, v176
	v_fmac_f32_e32 v148, v112, v80
	v_fmac_f32_e32 v149, v113, v81
	v_cvt_pk_bf16_f32 v148, v148, v149
	v_lshlrev_b32_e32 v149, 16, v177
	v_and_b32_e32 v150, 0xffff0000, v177
	v_fmac_f32_e32 v149, v114, v82
	v_fmac_f32_e32 v150, v115, v83
	v_cvt_pk_bf16_f32 v149, v149, v150
	v_lshlrev_b32_e32 v150, 16, v178
	v_and_b32_e32 v151, 0xffff0000, v178
	v_fmac_f32_e32 v150, v108, v76
	v_fmac_f32_e32 v151, v109, v77
	v_cvt_pk_bf16_f32 v150, v150, v151
	v_lshlrev_b32_e32 v151, 16, v179
	v_fmac_f32_e32 v151, v110, v78
	v_cvt_pk_bf16_f32 v151, v151, v164
	v_lshl_add_u64 v[164:165], s[14:15], 0, v[208:209]
	v_lshl_add_u64 v[164:165], v[164:165], 0, v[190:191]
	flat_store_dwordx4 v[164:165], v[148:151]
	s_nop 1
	v_lshlrev_b32_e32 v148, 16, v160
	v_and_b32_e32 v149, 0xffff0000, v160
	v_fmac_f32_e32 v148, v96, v64
	v_fmac_f32_e32 v149, v97, v65
	v_cvt_pk_bf16_f32 v148, v148, v149
	v_lshlrev_b32_e32 v149, 16, v161
	v_and_b32_e32 v150, 0xffff0000, v161
	v_fmac_f32_e32 v149, v98, v66
	v_fmac_f32_e32 v150, v99, v67
	v_cvt_pk_bf16_f32 v149, v149, v150
	v_lshlrev_b32_e32 v150, 16, v162
	v_and_b32_e32 v151, 0xffff0000, v162
	v_fmac_f32_e32 v150, v92, v60
	v_fmac_f32_e32 v151, v93, v61
	v_cvt_pk_bf16_f32 v150, v150, v151
	v_lshlrev_b32_e32 v151, 16, v163
	v_fmac_f32_e32 v151, v94, v62
	v_and_b32_e32 v160, 0xffff0000, v163
	v_fmac_f32_e32 v160, v95, v63
	v_cvt_pk_bf16_f32 v151, v151, v160
	flat_store_dwordx4 v[164:165], v[148:151] offset:256
	s_nop 1
	v_lshlrev_b32_e32 v148, 16, v156
	v_and_b32_e32 v149, 0xffff0000, v156
	v_fmac_f32_e32 v148, v104, v80
	v_fmac_f32_e32 v149, v105, v81
	v_cvt_pk_bf16_f32 v148, v148, v149
	v_lshlrev_b32_e32 v149, 16, v157
	v_and_b32_e32 v150, 0xffff0000, v157
	v_fmac_f32_e32 v149, v106, v82
	v_fmac_f32_e32 v150, v107, v83
	v_cvt_pk_bf16_f32 v149, v149, v150
	v_lshlrev_b32_e32 v150, 16, v158
	v_and_b32_e32 v151, 0xffff0000, v158
	v_fmac_f32_e32 v150, v100, v76
	v_fmac_f32_e32 v151, v101, v77
	v_cvt_pk_bf16_f32 v150, v150, v151
	v_lshlrev_b32_e32 v151, 16, v159
	v_and_b32_e32 v156, 0xffff0000, v159
	v_fmac_f32_e32 v151, v102, v78
	v_fmac_f32_e32 v156, v103, v79
	v_cvt_pk_bf16_f32 v151, v151, v156
	v_lshl_add_u64 v[156:157], s[14:15], 0, v[206:207]
	v_lshl_add_u64 v[156:157], v[156:157], 0, v[190:191]
	flat_store_dwordx4 v[156:157], v[148:151]
	s_nop 1
	v_lshlrev_b32_e32 v148, 16, v152
	v_and_b32_e32 v149, 0xffff0000, v152
	v_fmac_f32_e32 v148, v88, v64
	v_fmac_f32_e32 v149, v89, v65
	v_cvt_pk_bf16_f32 v148, v148, v149
	v_lshlrev_b32_e32 v149, 16, v153
	v_and_b32_e32 v150, 0xffff0000, v153
	v_fmac_f32_e32 v149, v90, v66
; __device__ __forceinline__ unsigned cvt_pk_bf16(float lo, float hi) { unsigned r; asm volatile("v_cvt_pk_bf16_f32 %0, %1, %2" : "=v"(r) : "v"(lo), "v"(hi)); return r; }
;     __device__ __forceinline__ void operator()(const f32x4 (&acc)[2][2][4][2], const Unit& u, int wr, int wc, int fr, int fq) const {
;     ...
;                 for (int m = 0; m < 4; ++m) { const size_t off = (size_t)(row0 + ai * HALF + m * 16) * ldc + col0;
; #pragma unroll
;                     for (int bj = 0; bj < 2; ++bj) bs[m][bj] = *(const u32x4*)(bp + off + bj * HALF); }
;     ...
;                 for (int m = 0; m < 4; ++m) { const size_t off = (size_t)(row0 + ai * HALF + m * 16) * ldc + col0;
; #pragma unroll
;                     for (int bj = 0; bj < 2; ++bj) { const u32x4 r = bs[m][bj]; const f32x4 a0 = acc[ai][bj][m][0], a1 = acc[ai][bj][m][1];
;                         u32x4 w;
;                         w.x = cvt_pk_bf16(__builtin_bit_cast(float, r.x << 16) + gv[bj][0][0] * a0[0], __builtin_bit_cast(float, r.x & 0xffff0000u) + gv[bj][0][1] * a0[1]);
;                         w.y = cvt_pk_bf16(__builtin_bit_cast(float, r.y << 16) + gv[bj][0][2] * a0[2], __builtin_bit_cast(float, r.y & 0xffff0000u) + gv[bj][0][3] * a0[3]);
;                         w.z = cvt_pk_bf16(__builtin_bit_cast(float, r.z << 16) + gv[bj][1][0] * a1[0], __builtin_bit_cast(float, r.z & 0xffff0000u) + gv[bj][1][1] * a1[1]);
;                         w.w = cvt_pk_bf16(__builtin_bit_cast(float, r.w << 16) + gv[bj][1][2] * a1[2], __builtin_bit_cast(float, r.w & 0xffff0000u) + gv[bj][1][3] * a1[3]);
;                         *(u32x4*)(out + off + bj * HALF) = w; } }
	v_fmac_f32_e32 v150, v91, v67
	v_cvt_pk_bf16_f32 v149, v149, v150
	v_lshlrev_b32_e32 v150, 16, v154
	v_and_b32_e32 v151, 0xffff0000, v154
	v_fmac_f32_e32 v150, v84, v60
	v_fmac_f32_e32 v151, v85, v61
	v_cvt_pk_bf16_f32 v150, v150, v151
	v_lshlrev_b32_e32 v151, 16, v155
	v_fmac_f32_e32 v151, v86, v62
	v_and_b32_e32 v152, 0xffff0000, v155
	v_fmac_f32_e32 v152, v87, v63
	v_cvt_pk_bf16_f32 v151, v151, v152
	flat_store_dwordx4 v[156:157], v[148:151] offset:256
	s_nop 1
	v_lshlrev_b64 v[148:149], 12, v[192:193]
	v_lshl_add_u64 v[206:207], v[148:149], 0, s[12:13]
	v_lshl_add_u64 v[150:151], v[204:205], 0, v[206:207]
	flat_load_dwordx4 v[152:155], v[150:151]
	flat_load_dwordx4 v[156:159], v[150:151] offset:256
	s_mov_b64 s[12:13], 0x90000
	v_lshl_add_u64 v[208:209], v[148:149], 0, s[12:13]
	v_lshl_add_u64 v[150:151], v[204:205], 0, v[208:209]
	flat_load_dwordx4 v[160:163], v[150:151]
	flat_load_dwordx4 v[164:167], v[150:151] offset:256
	s_mov_b64 s[12:13], 0xa0000
	v_lshl_add_u64 v[210:211], v[148:149], 0, s[12:13]
	v_lshl_add_u64 v[150:151], v[204:205], 0, v[210:211]
	flat_load_dwordx4 v[168:171], v[150:151]
	flat_load_dwordx4 v[172:175], v[150:151] offset:256
	s_mov_b64 s[12:13], 0xb0000
	v_lshl_add_u64 v[214:215], v[148:149], 0, s[12:13]
	v_lshl_add_u64 v[148:149], v[204:205], 0, v[214:215]
	flat_load_dwordx4 v[176:179], v[148:149]
	s_nop 0
	flat_load_dwordx4 v[148:151], v[148:149] offset:256
	v_lshl_add_u64 v[204:205], s[14:15], 0, v[206:207]
	v_lshl_add_u64 v[204:205], v[204:205], 0, v[190:191]
	s_waitcnt vmcnt(0) lgkmcnt(0)
; __device__ __forceinline__ unsigned cvt_pk_bf16(float lo, float hi) { unsigned r; asm volatile("v_cvt_pk_bf16_f32 %0, %1, %2" : "=v"(r) : "v"(lo), "v"(hi)); return r; }
;     __device__ __forceinline__ void operator()(const f32x4 (&acc)[2][2][4][2], const Unit& u, int wr, int wc, int fr, int fq) const {
;     ...
;                 for (int m = 0; m < 4; ++m) { const size_t off = (size_t)(row0 + ai * HALF + m * 16) * ldc + col0;
; #pragma unroll
;                     for (int bj = 0; bj < 2; ++bj) { const u32x4 r = bs[m][bj]; const f32x4 a0 = acc[ai][bj][m][0], a1 = acc[ai][bj][m][1];
;                         u32x4 w;
;                         w.x = cvt_pk_bf16(__builtin_bit_cast(float, r.x << 16) + gv[bj][0][0] * a0[0], __builtin_bit_cast(float, r.x & 0xffff0000u) + gv[bj][0][1] * a0[1]);
;                         w.y = cvt_pk_bf16(__builtin_bit_cast(float, r.y << 16) + gv[bj][0][2] * a0[2], __builtin_bit_cast(float, r.y & 0xffff0000u) + gv[bj][0][3] * a0[3]);
;                         w.z = cvt_pk_bf16(__builtin_bit_cast(float, r.z << 16) + gv[bj][1][0] * a1[0], __builtin_bit_cast(float, r.z & 0xffff0000u) + gv[bj][1][1] * a1[1]);
;                         w.w = cvt_pk_bf16(__builtin_bit_cast(float, r.w << 16) + gv[bj][1][2] * a1[2], __builtin_bit_cast(float, r.w & 0xffff0000u) + gv[bj][1][3] * a1[3]);
;                         *(u32x4*)(out + off + bj * HALF) = w; } }
;                 asm volatile("" ::: "memory"); }
; template <class Epi, class Sched, bool ALIGN_EPI = false, bool SP2 = false>
; __device__ __forceinline__ void gemm_phase(PG8_LAS unsigned char* lds, const Gemm g, const Sched& S, const Epi& E) {
;     ...
;         if (!has_next) break;
; #pragma unroll
;         for (int a = 0; a < 2; ++a)
; #pragma unroll
;             for (int b = 0; b < 2; ++b)
; #pragma unroll
;                 for (int m = 0; m < 4; ++m)
; #pragma unroll
;                     for (int n = 0; n < 2; ++n) acc[a][b][m][n] = (f32x4){0.f, 0.f, 0.f, 0.f};
;         cur = nxt; cA = nA; cB = nB; ++ui;
	v_lshlrev_b32_e32 v193, 16, v152
	v_and_b32_e32 v152, 0xffff0000, v152
	v_fmac_f32_e32 v193, v72, v80
	v_fmac_f32_e32 v152, v73, v81
	v_cvt_pk_bf16_f32 v152, v193, v152
	v_lshlrev_b32_e32 v193, 16, v153
	v_and_b32_e32 v153, 0xffff0000, v153
	v_fmac_f32_e32 v193, v74, v82
	v_fmac_f32_e32 v153, v75, v83
	v_cvt_pk_bf16_f32 v153, v193, v153
	v_lshlrev_b32_e32 v193, 16, v154
	v_and_b32_e32 v154, 0xffff0000, v154
	v_fmac_f32_e32 v193, v68, v76
	v_fmac_f32_e32 v154, v69, v77
	v_cvt_pk_bf16_f32 v154, v193, v154
	v_lshlrev_b32_e32 v193, 16, v155
	v_and_b32_e32 v155, 0xffff0000, v155
	v_fmac_f32_e32 v155, v71, v79
	v_fmac_f32_e32 v193, v70, v78
	v_cvt_pk_bf16_f32 v155, v193, v155
	flat_store_dwordx4 v[204:205], v[152:155]
	s_nop 1
	v_lshlrev_b32_e32 v152, 16, v156
	v_and_b32_e32 v153, 0xffff0000, v156
	v_fmac_f32_e32 v152, v48, v64
	v_fmac_f32_e32 v153, v49, v65
	v_cvt_pk_bf16_f32 v152, v152, v153
	v_lshlrev_b32_e32 v153, 16, v157
	v_and_b32_e32 v154, 0xffff0000, v157
	v_fmac_f32_e32 v153, v50, v66
	v_fmac_f32_e32 v154, v51, v67
	v_cvt_pk_bf16_f32 v153, v153, v154
	v_lshlrev_b32_e32 v154, 16, v158
	v_and_b32_e32 v155, 0xffff0000, v158
	v_fmac_f32_e32 v154, v44, v60
	v_fmac_f32_e32 v155, v45, v61
	v_cvt_pk_bf16_f32 v154, v154, v155
	v_lshlrev_b32_e32 v155, 16, v159
	v_fmac_f32_e32 v155, v46, v62
	v_and_b32_e32 v156, 0xffff0000, v159
	v_fmac_f32_e32 v156, v47, v63
	v_cvt_pk_bf16_f32 v155, v155, v156
	flat_store_dwordx4 v[204:205], v[152:155] offset:256
	v_and_b32_e32 v156, 0xffff0000, v163
	v_fmac_f32_e32 v156, v55, v79
	v_lshlrev_b32_e32 v152, 16, v160
	v_and_b32_e32 v153, 0xffff0000, v160
	v_fmac_f32_e32 v152, v56, v80
	v_fmac_f32_e32 v153, v57, v81
	v_cvt_pk_bf16_f32 v152, v152, v153
	v_lshlrev_b32_e32 v153, 16, v161
	v_and_b32_e32 v154, 0xffff0000, v161
	v_fmac_f32_e32 v153, v58, v82
	v_fmac_f32_e32 v154, v59, v83
	v_cvt_pk_bf16_f32 v153, v153, v154
	v_lshlrev_b32_e32 v154, 16, v162
	v_and_b32_e32 v155, 0xffff0000, v162
	v_fmac_f32_e32 v154, v52, v76
	v_fmac_f32_e32 v155, v53, v77
	v_cvt_pk_bf16_f32 v154, v154, v155
	v_lshlrev_b32_e32 v155, 16, v163
	v_fmac_f32_e32 v155, v54, v78
	v_cvt_pk_bf16_f32 v155, v155, v156
	v_lshl_add_u64 v[156:157], s[14:15], 0, v[208:209]
	v_lshl_add_u64 v[156:157], v[156:157], 0, v[190:191]
	flat_store_dwordx4 v[156:157], v[152:155]
	v_and_b32_e32 v158, 0xffff0000, v167
	v_fmac_f32_e32 v158, v39, v63
	v_lshlrev_b32_e32 v152, 16, v164
	v_and_b32_e32 v153, 0xffff0000, v164
	v_fmac_f32_e32 v152, v40, v64
	v_fmac_f32_e32 v153, v41, v65
	v_cvt_pk_bf16_f32 v152, v152, v153
	v_lshlrev_b32_e32 v153, 16, v165
	v_and_b32_e32 v154, 0xffff0000, v165
	v_fmac_f32_e32 v153, v42, v66
	v_fmac_f32_e32 v154, v43, v67
	v_cvt_pk_bf16_f32 v153, v153, v154
	v_lshlrev_b32_e32 v154, 16, v166
	v_and_b32_e32 v155, 0xffff0000, v166
	v_fmac_f32_e32 v154, v36, v60
	v_fmac_f32_e32 v155, v37, v61
	v_cvt_pk_bf16_f32 v154, v154, v155
	v_lshlrev_b32_e32 v155, 16, v167
	v_fmac_f32_e32 v155, v38, v62
	v_cvt_pk_bf16_f32 v155, v155, v158
	flat_store_dwordx4 v[156:157], v[152:155] offset:256
	v_and_b32_e32 v156, 0xffff0000, v171
	v_fmac_f32_e32 v156, v31, v79
	v_lshlrev_b32_e32 v152, 16, v168
	v_and_b32_e32 v153, 0xffff0000, v168
	v_fmac_f32_e32 v152, v32, v80
	v_fmac_f32_e32 v153, v33, v81
	v_cvt_pk_bf16_f32 v152, v152, v153
	v_lshlrev_b32_e32 v153, 16, v169
	v_and_b32_e32 v154, 0xffff0000, v169
	v_fmac_f32_e32 v153, v34, v82
	v_fmac_f32_e32 v154, v35, v83
	v_cvt_pk_bf16_f32 v153, v153, v154
	v_lshlrev_b32_e32 v154, 16, v170
	v_and_b32_e32 v155, 0xffff0000, v170
	v_fmac_f32_e32 v154, v28, v76
	v_fmac_f32_e32 v155, v29, v77
	v_cvt_pk_bf16_f32 v154, v154, v155
	v_lshlrev_b32_e32 v155, 16, v171
	v_fmac_f32_e32 v155, v30, v78
	v_cvt_pk_bf16_f32 v155, v155, v156
	v_lshl_add_u64 v[156:157], s[14:15], 0, v[210:211]
	v_lshl_add_u64 v[156:157], v[156:157], 0, v[190:191]
	flat_store_dwordx4 v[156:157], v[152:155]
	v_and_b32_e32 v158, 0xffff0000, v175
	v_fmac_f32_e32 v158, v15, v63
	v_lshlrev_b32_e32 v152, 16, v172
	v_and_b32_e32 v153, 0xffff0000, v172
	v_fmac_f32_e32 v152, v16, v64
	v_fmac_f32_e32 v153, v17, v65
	v_cvt_pk_bf16_f32 v152, v152, v153
	v_lshlrev_b32_e32 v153, 16, v173
	v_and_b32_e32 v154, 0xffff0000, v173
	v_fmac_f32_e32 v153, v18, v66
	v_fmac_f32_e32 v154, v19, v67
	v_cvt_pk_bf16_f32 v153, v153, v154
	v_lshlrev_b32_e32 v154, 16, v174
	v_and_b32_e32 v155, 0xffff0000, v174
	v_fmac_f32_e32 v154, v12, v60
	v_fmac_f32_e32 v155, v13, v61
	v_cvt_pk_bf16_f32 v154, v154, v155
	v_lshlrev_b32_e32 v155, 16, v175
	v_fmac_f32_e32 v155, v14, v62
	v_cvt_pk_bf16_f32 v155, v155, v158
	flat_store_dwordx4 v[156:157], v[152:155] offset:256
	v_and_b32_e32 v156, 0xffff0000, v179
	v_fmac_f32_e32 v156, v23, v79
	v_lshlrev_b32_e32 v152, 16, v176
	v_and_b32_e32 v153, 0xffff0000, v176
	v_fmac_f32_e32 v152, v24, v80
	v_fmac_f32_e32 v153, v25, v81
	v_cvt_pk_bf16_f32 v152, v152, v153
	v_lshlrev_b32_e32 v153, 16, v177
	v_and_b32_e32 v154, 0xffff0000, v177
	v_fmac_f32_e32 v153, v26, v82
	v_fmac_f32_e32 v154, v27, v83
	v_cvt_pk_bf16_f32 v153, v153, v154
	v_lshlrev_b32_e32 v154, 16, v178
	v_and_b32_e32 v155, 0xffff0000, v178
	v_fmac_f32_e32 v154, v20, v76
	v_fmac_f32_e32 v155, v21, v77
	v_cvt_pk_bf16_f32 v154, v154, v155
	v_lshlrev_b32_e32 v155, 16, v179
	v_fmac_f32_e32 v155, v22, v78
	v_cvt_pk_bf16_f32 v155, v155, v156
	v_lshl_add_u64 v[156:157], s[14:15], 0, v[214:215]
	v_lshl_add_u64 v[156:157], v[156:157], 0, v[190:191]
	flat_store_dwordx4 v[156:157], v[152:155]
	s_nop 1
	v_lshlrev_b32_e32 v152, 16, v148
	v_and_b32_e32 v148, 0xffff0000, v148
	v_fmac_f32_e32 v152, v8, v64
	v_fmac_f32_e32 v148, v9, v65
	v_cvt_pk_bf16_f32 v148, v152, v148
	v_lshlrev_b32_e32 v152, 16, v149
	v_and_b32_e32 v149, 0xffff0000, v149
	v_fmac_f32_e32 v152, v10, v66
	v_fmac_f32_e32 v149, v11, v67
	v_cvt_pk_bf16_f32 v149, v152, v149
	v_lshlrev_b32_e32 v152, 16, v150
	v_and_b32_e32 v150, 0xffff0000, v150
	v_fmac_f32_e32 v152, v4, v60
	v_fmac_f32_e32 v150, v5, v61
	v_cvt_pk_bf16_f32 v150, v152, v150
	v_lshlrev_b32_e32 v152, 16, v151
	v_and_b32_e32 v151, 0xffff0000, v151
	v_fmac_f32_e32 v151, v7, v63
	v_fmac_f32_e32 v152, v6, v62
	v_cvt_pk_bf16_f32 v151, v152, v151
	flat_store_dwordx4 v[156:157], v[148:151] offset:256
	s_cbranch_execnz .LBB0_2038
	s_branch .LBB0_2050
